# phase 10: relaxed first-iteration waits (vmcnt 24 at phase 4, counted wait before the phase-7 fragment read) placed only in the peeled first K iteration; on v092
# speedup vs baseline: 1.0017x; 1.0017x over previous
.LBB0_1092:
	s_ashr_i32 s37, s36, 31
	v_cmp_lt_i64_e32 vcc, s[0:1], v[142:143]
	s_lshl_b64 s[0:1], s[36:37], 19
	s_add_u32 s38, s68, s0
	s_addc_u32 s39, s69, s1
	s_and_b64 s[0:1], vcc, exec
	s_cselect_b32 s37, s39, s45
	s_cselect_b32 s60, s38, s44
	s_ashr_i32 s13, s12, 31
	s_lshl_b64 s[0:1], s[12:13], 19
	s_add_u32 s40, s70, s0
	s_addc_u32 s41, s71, s1
	s_and_b64 s[0:1], vcc, exec
	s_cselect_b32 s13, s41, s43
	s_cselect_b32 s61, s40, s42
	s_add_u32 s0, s44, 0x40080
	s_addc_u32 s1, s45, 0
	s_add_u32 s62, s42, 0x100
	s_addc_u32 s63, s43, 0
	s_mov_b32 s64, -2
	ds_read_b128 v[146:149], v167
	ds_read_b128 v[150:153], v167 offset:1024
	ds_read_b128 v[178:181], v167 offset:2048
	ds_read_b128 v[182:185], v167 offset:3072
	s_add_u32 s28, s0, 0xfffc0080
	s_addc_u32 s29, s1, -1
	s_cmp_eq_u32 s64, 12
	s_cselect_b32 s45, s37, s29
	s_cselect_b32 s44, s60, s28
	s_cselect_b32 s43, s13, s63
	s_cselect_b32 s42, s61, s62
	v_lshl_add_u64 v[156:157], s[0:1], 0, v[138:139]
	s_add_i32 m0, s47, 0xc000
	ds_read_b128 v[186:189], v171
	ds_read_b128 v[196:199], v171 offset:1024
	ds_read_b128 v[200:203], v171 offset:2048
	ds_read_b128 v[204:207], v171 offset:3072
	ds_read_b128 v[208:211], v171 offset:4096
	ds_read_b128 v[212:215], v171 offset:5120
	ds_read_b128 v[216:219], v171 offset:6144
	ds_read_b128 v[220:223], v171 offset:7168
	global_load_lds_dwordx4 v[156:157], off
	v_lshl_add_u64 v[156:157], s[0:1], 0, v[140:141]
	s_add_i32 m0, s47, 0xe000
	s_nop 0
	global_load_lds_dwordx4 v[156:157], off
	s_waitcnt lgkmcnt(8)
	s_barrier
	s_waitcnt lgkmcnt(0)
	v_mfma_f32_16x16x32_bf16 v[124:127], v[146:149], v[186:189], 0
	v_mfma_f32_16x16x32_bf16 v[120:123], v[178:181], v[186:189], 0
	v_mfma_f32_16x16x32_bf16 v[108:111], v[146:149], v[200:203], 0
	v_mfma_f32_16x16x32_bf16 v[104:107], v[178:181], v[200:203], 0
	v_mfma_f32_16x16x32_bf16 v[92:95], v[146:149], v[208:211], 0
	v_mfma_f32_16x16x32_bf16 v[88:91], v[178:181], v[208:211], 0
	v_mfma_f32_16x16x32_bf16 v[76:79], v[146:149], v[216:219], 0
	v_mfma_f32_16x16x32_bf16 v[72:75], v[178:181], v[216:219], 0
	v_mfma_f32_16x16x32_bf16 v[124:127], v[150:153], v[196:199], v[124:127]
	v_mfma_f32_16x16x32_bf16 v[120:123], v[182:185], v[196:199], v[120:123]
	v_mfma_f32_16x16x32_bf16 v[108:111], v[150:153], v[204:207], v[108:111]
	v_mfma_f32_16x16x32_bf16 v[104:107], v[182:185], v[204:207], v[104:107]
	v_mfma_f32_16x16x32_bf16 v[92:95], v[150:153], v[212:215], v[92:95]
	v_mfma_f32_16x16x32_bf16 v[88:91], v[182:185], v[212:215], v[88:91]
	v_mfma_f32_16x16x32_bf16 v[76:79], v[150:153], v[220:223], v[76:79]
	v_mfma_f32_16x16x32_bf16 v[72:75], v[182:185], v[220:223], v[72:75]
	s_barrier
	s_add_i32 s28, s56, s11
	v_lshl_add_u64 v[156:157], s[42:43], 0, v[132:133]
	s_mov_b32 m0, s28
	ds_read_b128 v[224:227], v175
	ds_read_b128 v[228:231], v175 offset:1024
	ds_read_b128 v[232:235], v175 offset:2048
	ds_read_b128 v[236:239], v175 offset:3072
	global_load_lds_dwordx4 v[156:157], off
	v_lshl_add_u64 v[160:161], s[42:43], 0, v[128:129]
	s_add_i32 m0, s28, 0x2000
	s_nop 0
	global_load_lds_dwordx4 v[160:161], off
	s_barrier
	s_waitcnt lgkmcnt(0)
	v_mfma_f32_16x16x32_bf16 v[116:119], v[224:227], v[186:189], 0
	v_mfma_f32_16x16x32_bf16 v[112:115], v[232:235], v[186:189], 0
	v_mfma_f32_16x16x32_bf16 v[100:103], v[224:227], v[200:203], 0
	v_mfma_f32_16x16x32_bf16 v[96:99], v[232:235], v[200:203], 0
	v_mfma_f32_16x16x32_bf16 v[84:87], v[224:227], v[208:211], 0
	v_mfma_f32_16x16x32_bf16 v[80:83], v[232:235], v[208:211], 0
	v_mfma_f32_16x16x32_bf16 v[68:71], v[224:227], v[216:219], 0
	v_mfma_f32_16x16x32_bf16 v[64:67], v[232:235], v[216:219], 0
	v_mfma_f32_16x16x32_bf16 v[116:119], v[228:231], v[196:199], v[116:119]
	v_mfma_f32_16x16x32_bf16 v[112:115], v[236:239], v[196:199], v[112:115]
	v_mfma_f32_16x16x32_bf16 v[100:103], v[228:231], v[204:207], v[100:103]
	v_mfma_f32_16x16x32_bf16 v[96:99], v[236:239], v[204:207], v[96:99]
	v_mfma_f32_16x16x32_bf16 v[84:87], v[228:231], v[212:215], v[84:87]
	v_mfma_f32_16x16x32_bf16 v[80:83], v[236:239], v[212:215], v[80:83]
	v_mfma_f32_16x16x32_bf16 v[68:71], v[228:231], v[220:223], v[68:71]
	v_mfma_f32_16x16x32_bf16 v[64:67], v[236:239], v[220:223], v[64:67]
	s_mov_b32 m0, s47
	v_lshl_add_u64 v[164:165], s[44:45], 0, v[134:135]
	s_barrier
	ds_read_b128 v[186:189], v171 offset:16384
	ds_read_b128 v[196:199], v171 offset:17408
	ds_read_b128 v[200:203], v171 offset:18432
	ds_read_b128 v[204:207], v171 offset:19456
	ds_read_b128 v[208:211], v171 offset:20480
	ds_read_b128 v[212:215], v171 offset:21504
	ds_read_b128 v[216:219], v171 offset:22528
	ds_read_b128 v[220:223], v171 offset:23552
	global_load_lds_dwordx4 v[164:165], off
	v_lshl_add_u64 v[168:169], s[44:45], 0, v[130:131]
	s_mov_b32 m0, s48
	s_nop 0
	global_load_lds_dwordx4 v[168:169], off
	s_barrier
	s_waitcnt lgkmcnt(0)
	v_mfma_f32_16x16x32_bf16 v[60:63], v[146:149], v[186:189], 0
	v_mfma_f32_16x16x32_bf16 v[56:59], v[178:181], v[186:189], 0
	v_mfma_f32_16x16x32_bf16 v[44:47], v[146:149], v[200:203], 0
	v_mfma_f32_16x16x32_bf16 v[40:43], v[178:181], v[200:203], 0
	v_mfma_f32_16x16x32_bf16 v[28:31], v[146:149], v[208:211], 0
	v_mfma_f32_16x16x32_bf16 v[24:27], v[178:181], v[208:211], 0
	v_mfma_f32_16x16x32_bf16 v[12:15], v[146:149], v[216:219], 0
	v_mfma_f32_16x16x32_bf16 v[8:11], v[178:181], v[216:219], 0
	v_mfma_f32_16x16x32_bf16 v[60:63], v[150:153], v[196:199], v[60:63]
	v_mfma_f32_16x16x32_bf16 v[56:59], v[182:185], v[196:199], v[56:59]
	v_mfma_f32_16x16x32_bf16 v[44:47], v[150:153], v[204:207], v[44:47]
	v_mfma_f32_16x16x32_bf16 v[40:43], v[182:185], v[204:207], v[40:43]
	v_mfma_f32_16x16x32_bf16 v[28:31], v[150:153], v[212:215], v[28:31]
	v_mfma_f32_16x16x32_bf16 v[24:27], v[182:185], v[212:215], v[24:27]
	v_mfma_f32_16x16x32_bf16 v[12:15], v[150:153], v[220:223], v[12:15]
	v_mfma_f32_16x16x32_bf16 v[8:11], v[182:185], v[220:223], v[8:11]
	s_barrier
	s_add_u32 s66, s42, 0x40000
	s_addc_u32 s67, s43, 0
	s_add_i32 s28, s57, s11
	v_lshl_add_u64 v[146:147], s[66:67], 0, v[132:133]
	s_mov_b32 m0, s28
	s_nop 0
	global_load_lds_dwordx4 v[146:147], off
	v_lshl_add_u64 v[146:147], s[66:67], 0, v[128:129]
	s_add_i32 m0, s28, 0x2000
	s_nop 0
	global_load_lds_dwordx4 v[146:147], off
	s_cmp_eq_u32 s98, 0
	s_cbranch_scc1 .Lk10_w4n
	s_mov_b32 s98, 0
	s_waitcnt vmcnt(24)
	s_branch .Lk10_w4j

.Lk10_w4j:
	s_barrier
	v_mfma_f32_16x16x32_bf16 v[52:55], v[224:227], v[186:189], 0
	v_mfma_f32_16x16x32_bf16 v[48:51], v[232:235], v[186:189], 0
	v_mfma_f32_16x16x32_bf16 v[36:39], v[224:227], v[200:203], 0
	v_mfma_f32_16x16x32_bf16 v[32:35], v[232:235], v[200:203], 0
	v_mfma_f32_16x16x32_bf16 v[20:23], v[224:227], v[208:211], 0
	v_mfma_f32_16x16x32_bf16 v[16:19], v[232:235], v[208:211], 0
	v_mfma_f32_16x16x32_bf16 v[4:7], v[224:227], v[216:219], 0
	v_mfma_f32_16x16x32_bf16 v[0:3], v[232:235], v[216:219], 0
	v_mfma_f32_16x16x32_bf16 v[52:55], v[228:231], v[196:199], v[52:55]
	v_mfma_f32_16x16x32_bf16 v[48:51], v[236:239], v[196:199], v[48:51]
	v_mfma_f32_16x16x32_bf16 v[36:39], v[228:231], v[204:207], v[36:39]
	v_mfma_f32_16x16x32_bf16 v[32:35], v[236:239], v[204:207], v[32:35]
	v_mfma_f32_16x16x32_bf16 v[20:23], v[228:231], v[212:215], v[20:23]
	v_mfma_f32_16x16x32_bf16 v[16:19], v[236:239], v[212:215], v[16:19]
	v_mfma_f32_16x16x32_bf16 v[4:7], v[228:231], v[220:223], v[4:7]
	v_mfma_f32_16x16x32_bf16 v[0:3], v[236:239], v[220:223], v[0:3]
	s_add_i32 s28, 0, 0x18000
	v_add_u32_e32 v154, s28, v159
	s_barrier
	ds_read_b128 v[146:149], v154
	ds_read_b128 v[150:153], v154 offset:1024
	ds_read_b128 v[178:181], v154 offset:2048
	ds_read_b128 v[182:185], v154 offset:3072
	s_add_u32 s44, s44, 0x40000
	s_addc_u32 s45, s45, 0
	s_mov_b32 m0, s49
	v_lshl_add_u64 v[172:173], s[44:45], 0, v[134:135]
	ds_read_b128 v[186:189], v171 offset:32768
	ds_read_b128 v[196:199], v171 offset:33792
	ds_read_b128 v[200:203], v171 offset:34816
	ds_read_b128 v[204:207], v171 offset:35840
	ds_read_b128 v[208:211], v171 offset:36864
	ds_read_b128 v[212:215], v171 offset:37888
	ds_read_b128 v[216:219], v171 offset:38912
	ds_read_b128 v[220:223], v171 offset:39936
	global_load_lds_dwordx4 v[172:173], off
	v_lshl_add_u64 v[172:173], s[44:45], 0, v[130:131]
	s_mov_b32 m0, s50
	s_nop 0
	global_load_lds_dwordx4 v[172:173], off
	s_waitcnt lgkmcnt(8)
	s_barrier
	s_waitcnt lgkmcnt(0)
	v_mfma_f32_16x16x32_bf16 v[124:127], v[146:149], v[186:189], v[124:127]
	v_mfma_f32_16x16x32_bf16 v[120:123], v[178:181], v[186:189], v[120:123]
	v_mfma_f32_16x16x32_bf16 v[108:111], v[146:149], v[200:203], v[108:111]
	v_mfma_f32_16x16x32_bf16 v[104:107], v[178:181], v[200:203], v[104:107]
	v_mfma_f32_16x16x32_bf16 v[92:95], v[146:149], v[208:211], v[92:95]
	v_mfma_f32_16x16x32_bf16 v[88:91], v[178:181], v[208:211], v[88:91]
	v_mfma_f32_16x16x32_bf16 v[76:79], v[146:149], v[216:219], v[76:79]
	v_mfma_f32_16x16x32_bf16 v[72:75], v[178:181], v[216:219], v[72:75]
	v_mfma_f32_16x16x32_bf16 v[124:127], v[150:153], v[196:199], v[124:127]
	v_mfma_f32_16x16x32_bf16 v[120:123], v[182:185], v[196:199], v[120:123]
	v_mfma_f32_16x16x32_bf16 v[108:111], v[150:153], v[204:207], v[108:111]
	v_mfma_f32_16x16x32_bf16 v[104:107], v[182:185], v[204:207], v[104:107]
	v_mfma_f32_16x16x32_bf16 v[92:95], v[150:153], v[212:215], v[92:95]
	v_mfma_f32_16x16x32_bf16 v[88:91], v[182:185], v[212:215], v[88:91]
	v_mfma_f32_16x16x32_bf16 v[76:79], v[150:153], v[220:223], v[76:79]
	v_mfma_f32_16x16x32_bf16 v[72:75], v[182:185], v[220:223], v[72:75]
	s_barrier
	s_add_i32 s29, 0, 0x1c000
	s_add_i32 s28, s28, s11
	v_add_u32_e32 v154, s29, v159
	v_lshl_add_u64 v[156:157], v[156:157], 0, s[6:7]
	s_mov_b32 m0, s28
	ds_read_b128 v[224:227], v154
	ds_read_b128 v[228:231], v154 offset:1024
	ds_read_b128 v[232:235], v154 offset:2048
	ds_read_b128 v[236:239], v154 offset:3072
	global_load_lds_dwordx4 v[156:157], off
	v_lshl_add_u64 v[156:157], v[160:161], 0, s[6:7]
	s_add_i32 m0, s28, 0x2000
	s_nop 0
	global_load_lds_dwordx4 v[156:157], off
	s_barrier
	s_waitcnt lgkmcnt(0)
	v_mfma_f32_16x16x32_bf16 v[116:119], v[224:227], v[186:189], v[116:119]
	v_mfma_f32_16x16x32_bf16 v[112:115], v[232:235], v[186:189], v[112:115]
	v_mfma_f32_16x16x32_bf16 v[100:103], v[224:227], v[200:203], v[100:103]
	v_mfma_f32_16x16x32_bf16 v[96:99], v[232:235], v[200:203], v[96:99]
	v_mfma_f32_16x16x32_bf16 v[84:87], v[224:227], v[208:211], v[84:87]
	v_mfma_f32_16x16x32_bf16 v[80:83], v[232:235], v[208:211], v[80:83]
	v_mfma_f32_16x16x32_bf16 v[68:71], v[224:227], v[216:219], v[68:71]
	v_mfma_f32_16x16x32_bf16 v[64:67], v[232:235], v[216:219], v[64:67]
	v_mfma_f32_16x16x32_bf16 v[116:119], v[228:231], v[196:199], v[116:119]
	v_mfma_f32_16x16x32_bf16 v[112:115], v[236:239], v[196:199], v[112:115]
	v_mfma_f32_16x16x32_bf16 v[100:103], v[228:231], v[204:207], v[100:103]
	v_mfma_f32_16x16x32_bf16 v[96:99], v[236:239], v[204:207], v[96:99]
	v_mfma_f32_16x16x32_bf16 v[84:87], v[228:231], v[212:215], v[84:87]
	v_mfma_f32_16x16x32_bf16 v[80:83], v[236:239], v[212:215], v[80:83]
	v_mfma_f32_16x16x32_bf16 v[68:71], v[228:231], v[220:223], v[68:71]
	v_mfma_f32_16x16x32_bf16 v[64:67], v[236:239], v[220:223], v[64:67]
	s_mov_b32 m0, s53
	v_lshl_add_u64 v[156:157], v[164:165], 0, s[6:7]
	s_waitcnt vmcnt(10)
	s_barrier
	ds_read_b128 v[186:189], v171 offset:49152
	ds_read_b128 v[196:199], v171 offset:50176
	ds_read_b128 v[200:203], v171 offset:51200
	ds_read_b128 v[204:207], v171 offset:52224
	ds_read_b128 v[208:211], v171 offset:53248
	ds_read_b128 v[212:215], v171 offset:54272
	ds_read_b128 v[216:219], v171 offset:55296
	ds_read_b128 v[220:223], v171 offset:56320
	global_load_lds_dwordx4 v[156:157], off
	v_lshl_add_u64 v[156:157], v[168:169], 0, s[6:7]
	s_mov_b32 m0, s54
	s_nop 0
	global_load_lds_dwordx4 v[156:157], off
	s_barrier
	s_waitcnt lgkmcnt(0)
	v_mfma_f32_16x16x32_bf16 v[60:63], v[146:149], v[186:189], v[60:63]
	v_mfma_f32_16x16x32_bf16 v[56:59], v[178:181], v[186:189], v[56:59]
	v_mfma_f32_16x16x32_bf16 v[44:47], v[146:149], v[200:203], v[44:47]
	v_mfma_f32_16x16x32_bf16 v[40:43], v[178:181], v[200:203], v[40:43]
	v_mfma_f32_16x16x32_bf16 v[28:31], v[146:149], v[208:211], v[28:31]
	v_mfma_f32_16x16x32_bf16 v[24:27], v[178:181], v[208:211], v[24:27]
	v_mfma_f32_16x16x32_bf16 v[12:15], v[146:149], v[216:219], v[12:15]
	v_mfma_f32_16x16x32_bf16 v[8:11], v[178:181], v[216:219], v[8:11]
	v_mfma_f32_16x16x32_bf16 v[60:63], v[150:153], v[196:199], v[60:63]
	v_mfma_f32_16x16x32_bf16 v[56:59], v[182:185], v[196:199], v[56:59]
	v_mfma_f32_16x16x32_bf16 v[44:47], v[150:153], v[204:207], v[44:47]
	v_mfma_f32_16x16x32_bf16 v[40:43], v[182:185], v[204:207], v[40:43]
	v_mfma_f32_16x16x32_bf16 v[28:31], v[150:153], v[212:215], v[28:31]
	v_mfma_f32_16x16x32_bf16 v[24:27], v[182:185], v[212:215], v[24:27]
	v_mfma_f32_16x16x32_bf16 v[12:15], v[150:153], v[220:223], v[12:15]
	v_mfma_f32_16x16x32_bf16 v[8:11], v[182:185], v[220:223], v[8:11]
	s_barrier
	s_add_u32 s42, s42, 0x40080
	s_addc_u32 s43, s43, 0
	s_add_i32 s28, s29, s11
	v_lshl_add_u64 v[146:147], s[42:43], 0, v[132:133]
	s_mov_b32 m0, s28
	s_nop 0
	global_load_lds_dwordx4 v[146:147], off
	v_lshl_add_u64 v[146:147], s[42:43], 0, v[128:129]
	s_add_i32 m0, s28, 0x2000
	s_nop 0
	global_load_lds_dwordx4 v[146:147], off
	s_waitcnt vmcnt(6)
	s_barrier
	v_mfma_f32_16x16x32_bf16 v[52:55], v[224:227], v[186:189], v[52:55]
	v_mfma_f32_16x16x32_bf16 v[48:51], v[232:235], v[186:189], v[48:51]
	v_mfma_f32_16x16x32_bf16 v[36:39], v[224:227], v[200:203], v[36:39]
	v_mfma_f32_16x16x32_bf16 v[32:35], v[232:235], v[200:203], v[32:35]
	v_mfma_f32_16x16x32_bf16 v[20:23], v[224:227], v[208:211], v[20:23]
	v_mfma_f32_16x16x32_bf16 v[16:19], v[232:235], v[208:211], v[16:19]
	v_mfma_f32_16x16x32_bf16 v[4:7], v[224:227], v[216:219], v[4:7]
	v_mfma_f32_16x16x32_bf16 v[0:3], v[232:235], v[216:219], v[0:3]
	v_mfma_f32_16x16x32_bf16 v[52:55], v[228:231], v[196:199], v[52:55]
	v_mfma_f32_16x16x32_bf16 v[48:51], v[236:239], v[196:199], v[48:51]
	v_mfma_f32_16x16x32_bf16 v[36:39], v[228:231], v[204:207], v[36:39]
	v_mfma_f32_16x16x32_bf16 v[32:35], v[236:239], v[204:207], v[32:35]
	v_mfma_f32_16x16x32_bf16 v[20:23], v[228:231], v[212:215], v[20:23]
	v_mfma_f32_16x16x32_bf16 v[16:19], v[236:239], v[212:215], v[16:19]
	v_mfma_f32_16x16x32_bf16 v[4:7], v[228:231], v[220:223], v[4:7]
	v_mfma_f32_16x16x32_bf16 v[0:3], v[236:239], v[220:223], v[0:3]
	s_add_i32 s64, s64, 2
	s_add_u32 s0, s0, 0x100
	s_addc_u32 s1, s1, 0
	s_add_u32 s62, s62, 0x100
	s_addc_u32 s63, s63, 0
	s_cmp_gt_u32 s64, 13
	s_barrier
	s_cbranch_scc0 .LBB0_1093
.LBB0_1093:
	ds_read_b128 v[146:149], v167
	ds_read_b128 v[150:153], v167 offset:1024
	ds_read_b128 v[178:181], v167 offset:2048
	ds_read_b128 v[182:185], v167 offset:3072
	s_add_u32 s28, s0, 0xfffc0080
	s_addc_u32 s29, s1, -1
	s_cmp_eq_u32 s64, 12
	s_cselect_b32 s45, s37, s29
	s_cselect_b32 s44, s60, s28
	s_cselect_b32 s43, s13, s63
	s_cselect_b32 s42, s61, s62
	v_lshl_add_u64 v[156:157], s[0:1], 0, v[138:139]
	s_add_i32 m0, s47, 0xc000
	ds_read_b128 v[186:189], v171
	ds_read_b128 v[196:199], v171 offset:1024
	ds_read_b128 v[200:203], v171 offset:2048
	ds_read_b128 v[204:207], v171 offset:3072
	ds_read_b128 v[208:211], v171 offset:4096
	ds_read_b128 v[212:215], v171 offset:5120
	ds_read_b128 v[216:219], v171 offset:6144
	ds_read_b128 v[220:223], v171 offset:7168
	global_load_lds_dwordx4 v[156:157], off
	v_lshl_add_u64 v[156:157], s[0:1], 0, v[140:141]
	s_add_i32 m0, s47, 0xe000
	s_nop 0
	global_load_lds_dwordx4 v[156:157], off
	s_waitcnt lgkmcnt(8)
	s_barrier
	s_waitcnt lgkmcnt(0)
	v_mfma_f32_16x16x32_bf16 v[124:127], v[146:149], v[186:189], v[124:127]
	v_mfma_f32_16x16x32_bf16 v[120:123], v[178:181], v[186:189], v[120:123]
	v_mfma_f32_16x16x32_bf16 v[108:111], v[146:149], v[200:203], v[108:111]
	v_mfma_f32_16x16x32_bf16 v[104:107], v[178:181], v[200:203], v[104:107]
	v_mfma_f32_16x16x32_bf16 v[92:95], v[146:149], v[208:211], v[92:95]
	v_mfma_f32_16x16x32_bf16 v[88:91], v[178:181], v[208:211], v[88:91]
	v_mfma_f32_16x16x32_bf16 v[76:79], v[146:149], v[216:219], v[76:79]
	v_mfma_f32_16x16x32_bf16 v[72:75], v[178:181], v[216:219], v[72:75]
	v_mfma_f32_16x16x32_bf16 v[124:127], v[150:153], v[196:199], v[124:127]
	v_mfma_f32_16x16x32_bf16 v[120:123], v[182:185], v[196:199], v[120:123]
	v_mfma_f32_16x16x32_bf16 v[108:111], v[150:153], v[204:207], v[108:111]
	v_mfma_f32_16x16x32_bf16 v[104:107], v[182:185], v[204:207], v[104:107]
	v_mfma_f32_16x16x32_bf16 v[92:95], v[150:153], v[212:215], v[92:95]
	v_mfma_f32_16x16x32_bf16 v[88:91], v[182:185], v[212:215], v[88:91]
	v_mfma_f32_16x16x32_bf16 v[76:79], v[150:153], v[220:223], v[76:79]
	v_mfma_f32_16x16x32_bf16 v[72:75], v[182:185], v[220:223], v[72:75]
	s_barrier
	s_add_i32 s28, s56, s11
	v_lshl_add_u64 v[156:157], s[42:43], 0, v[132:133]
	s_mov_b32 m0, s28
	ds_read_b128 v[224:227], v175
	ds_read_b128 v[228:231], v175 offset:1024
	ds_read_b128 v[232:235], v175 offset:2048
	ds_read_b128 v[236:239], v175 offset:3072
	global_load_lds_dwordx4 v[156:157], off
	v_lshl_add_u64 v[160:161], s[42:43], 0, v[128:129]
	s_add_i32 m0, s28, 0x2000
	s_nop 0
	global_load_lds_dwordx4 v[160:161], off
	s_barrier
	s_waitcnt lgkmcnt(0)
	v_mfma_f32_16x16x32_bf16 v[116:119], v[224:227], v[186:189], v[116:119]
	v_mfma_f32_16x16x32_bf16 v[112:115], v[232:235], v[186:189], v[112:115]
	v_mfma_f32_16x16x32_bf16 v[100:103], v[224:227], v[200:203], v[100:103]
	v_mfma_f32_16x16x32_bf16 v[96:99], v[232:235], v[200:203], v[96:99]
	v_mfma_f32_16x16x32_bf16 v[84:87], v[224:227], v[208:211], v[84:87]
	v_mfma_f32_16x16x32_bf16 v[80:83], v[232:235], v[208:211], v[80:83]
	v_mfma_f32_16x16x32_bf16 v[68:71], v[224:227], v[216:219], v[68:71]
	v_mfma_f32_16x16x32_bf16 v[64:67], v[232:235], v[216:219], v[64:67]
	v_mfma_f32_16x16x32_bf16 v[116:119], v[228:231], v[196:199], v[116:119]
	v_mfma_f32_16x16x32_bf16 v[112:115], v[236:239], v[196:199], v[112:115]
	v_mfma_f32_16x16x32_bf16 v[100:103], v[228:231], v[204:207], v[100:103]
	v_mfma_f32_16x16x32_bf16 v[96:99], v[236:239], v[204:207], v[96:99]
	v_mfma_f32_16x16x32_bf16 v[84:87], v[228:231], v[212:215], v[84:87]
	v_mfma_f32_16x16x32_bf16 v[80:83], v[236:239], v[212:215], v[80:83]
	v_mfma_f32_16x16x32_bf16 v[68:71], v[228:231], v[220:223], v[68:71]
	v_mfma_f32_16x16x32_bf16 v[64:67], v[236:239], v[220:223], v[64:67]
	s_mov_b32 m0, s47
	v_lshl_add_u64 v[164:165], s[44:45], 0, v[134:135]
	s_barrier
	ds_read_b128 v[186:189], v171 offset:16384
	ds_read_b128 v[196:199], v171 offset:17408
	ds_read_b128 v[200:203], v171 offset:18432
	ds_read_b128 v[204:207], v171 offset:19456
	ds_read_b128 v[208:211], v171 offset:20480
	ds_read_b128 v[212:215], v171 offset:21504
	ds_read_b128 v[216:219], v171 offset:22528
	ds_read_b128 v[220:223], v171 offset:23552
	global_load_lds_dwordx4 v[164:165], off
	v_lshl_add_u64 v[168:169], s[44:45], 0, v[130:131]
	s_mov_b32 m0, s48
	s_nop 0
	global_load_lds_dwordx4 v[168:169], off
	s_barrier
	s_waitcnt lgkmcnt(0)
	v_mfma_f32_16x16x32_bf16 v[60:63], v[146:149], v[186:189], v[60:63]
	v_mfma_f32_16x16x32_bf16 v[56:59], v[178:181], v[186:189], v[56:59]
	v_mfma_f32_16x16x32_bf16 v[44:47], v[146:149], v[200:203], v[44:47]
	v_mfma_f32_16x16x32_bf16 v[40:43], v[178:181], v[200:203], v[40:43]
	v_mfma_f32_16x16x32_bf16 v[28:31], v[146:149], v[208:211], v[28:31]
	v_mfma_f32_16x16x32_bf16 v[24:27], v[178:181], v[208:211], v[24:27]
	v_mfma_f32_16x16x32_bf16 v[12:15], v[146:149], v[216:219], v[12:15]
	v_mfma_f32_16x16x32_bf16 v[8:11], v[178:181], v[216:219], v[8:11]
	v_mfma_f32_16x16x32_bf16 v[60:63], v[150:153], v[196:199], v[60:63]
	v_mfma_f32_16x16x32_bf16 v[56:59], v[182:185], v[196:199], v[56:59]
	v_mfma_f32_16x16x32_bf16 v[44:47], v[150:153], v[204:207], v[44:47]
	v_mfma_f32_16x16x32_bf16 v[40:43], v[182:185], v[204:207], v[40:43]
	v_mfma_f32_16x16x32_bf16 v[28:31], v[150:153], v[212:215], v[28:31]
	v_mfma_f32_16x16x32_bf16 v[24:27], v[182:185], v[212:215], v[24:27]
	v_mfma_f32_16x16x32_bf16 v[12:15], v[150:153], v[220:223], v[12:15]
	v_mfma_f32_16x16x32_bf16 v[8:11], v[182:185], v[220:223], v[8:11]
	s_barrier
	s_add_u32 s66, s42, 0x40000
	s_addc_u32 s67, s43, 0
	s_add_i32 s28, s57, s11
	v_lshl_add_u64 v[146:147], s[66:67], 0, v[132:133]
	s_mov_b32 m0, s28
	s_nop 0
	global_load_lds_dwordx4 v[146:147], off
	v_lshl_add_u64 v[146:147], s[66:67], 0, v[128:129]
	s_add_i32 m0, s28, 0x2000
	s_nop 0
	global_load_lds_dwordx4 v[146:147], off
	s_waitcnt vmcnt(6)
	s_barrier
	v_mfma_f32_16x16x32_bf16 v[52:55], v[224:227], v[186:189], v[52:55]
	v_mfma_f32_16x16x32_bf16 v[48:51], v[232:235], v[186:189], v[48:51]
	v_mfma_f32_16x16x32_bf16 v[36:39], v[224:227], v[200:203], v[36:39]
	v_mfma_f32_16x16x32_bf16 v[32:35], v[232:235], v[200:203], v[32:35]
	v_mfma_f32_16x16x32_bf16 v[20:23], v[224:227], v[208:211], v[20:23]
	v_mfma_f32_16x16x32_bf16 v[16:19], v[232:235], v[208:211], v[16:19]
	v_mfma_f32_16x16x32_bf16 v[4:7], v[224:227], v[216:219], v[4:7]
	v_mfma_f32_16x16x32_bf16 v[0:3], v[232:235], v[216:219], v[0:3]
	v_mfma_f32_16x16x32_bf16 v[52:55], v[228:231], v[196:199], v[52:55]
	v_mfma_f32_16x16x32_bf16 v[48:51], v[236:239], v[196:199], v[48:51]
	v_mfma_f32_16x16x32_bf16 v[36:39], v[228:231], v[204:207], v[36:39]
	v_mfma_f32_16x16x32_bf16 v[32:35], v[236:239], v[204:207], v[32:35]
	v_mfma_f32_16x16x32_bf16 v[20:23], v[228:231], v[212:215], v[20:23]
	v_mfma_f32_16x16x32_bf16 v[16:19], v[236:239], v[212:215], v[16:19]
	v_mfma_f32_16x16x32_bf16 v[4:7], v[228:231], v[220:223], v[4:7]
	v_mfma_f32_16x16x32_bf16 v[0:3], v[236:239], v[220:223], v[0:3]
	s_add_i32 s28, 0, 0x18000
	v_add_u32_e32 v154, s28, v159
	s_barrier
	ds_read_b128 v[146:149], v154
	ds_read_b128 v[150:153], v154 offset:1024
	ds_read_b128 v[178:181], v154 offset:2048
	ds_read_b128 v[182:185], v154 offset:3072
	s_add_u32 s44, s44, 0x40000
	s_addc_u32 s45, s45, 0
	s_mov_b32 m0, s49
	v_lshl_add_u64 v[172:173], s[44:45], 0, v[134:135]
	ds_read_b128 v[186:189], v171 offset:32768
	ds_read_b128 v[196:199], v171 offset:33792
	ds_read_b128 v[200:203], v171 offset:34816
	ds_read_b128 v[204:207], v171 offset:35840
	ds_read_b128 v[208:211], v171 offset:36864
	ds_read_b128 v[212:215], v171 offset:37888
	ds_read_b128 v[216:219], v171 offset:38912
	ds_read_b128 v[220:223], v171 offset:39936
	global_load_lds_dwordx4 v[172:173], off
	v_lshl_add_u64 v[172:173], s[44:45], 0, v[130:131]
	s_mov_b32 m0, s50
	s_nop 0
	global_load_lds_dwordx4 v[172:173], off
	s_waitcnt lgkmcnt(8)
	s_barrier
	s_waitcnt lgkmcnt(0)
	v_mfma_f32_16x16x32_bf16 v[124:127], v[146:149], v[186:189], v[124:127]
	v_mfma_f32_16x16x32_bf16 v[120:123], v[178:181], v[186:189], v[120:123]
	v_mfma_f32_16x16x32_bf16 v[108:111], v[146:149], v[200:203], v[108:111]
	v_mfma_f32_16x16x32_bf16 v[104:107], v[178:181], v[200:203], v[104:107]
	v_mfma_f32_16x16x32_bf16 v[92:95], v[146:149], v[208:211], v[92:95]
	v_mfma_f32_16x16x32_bf16 v[88:91], v[178:181], v[208:211], v[88:91]
	v_mfma_f32_16x16x32_bf16 v[76:79], v[146:149], v[216:219], v[76:79]
	v_mfma_f32_16x16x32_bf16 v[72:75], v[178:181], v[216:219], v[72:75]
	v_mfma_f32_16x16x32_bf16 v[124:127], v[150:153], v[196:199], v[124:127]
	v_mfma_f32_16x16x32_bf16 v[120:123], v[182:185], v[196:199], v[120:123]
	v_mfma_f32_16x16x32_bf16 v[108:111], v[150:153], v[204:207], v[108:111]
	v_mfma_f32_16x16x32_bf16 v[104:107], v[182:185], v[204:207], v[104:107]
	v_mfma_f32_16x16x32_bf16 v[92:95], v[150:153], v[212:215], v[92:95]
	v_mfma_f32_16x16x32_bf16 v[88:91], v[182:185], v[212:215], v[88:91]
	v_mfma_f32_16x16x32_bf16 v[76:79], v[150:153], v[220:223], v[76:79]
	v_mfma_f32_16x16x32_bf16 v[72:75], v[182:185], v[220:223], v[72:75]
	s_barrier
	s_add_i32 s29, 0, 0x1c000
	s_add_i32 s28, s28, s11
	v_add_u32_e32 v154, s29, v159
	v_lshl_add_u64 v[156:157], v[156:157], 0, s[6:7]
	s_mov_b32 m0, s28
	ds_read_b128 v[224:227], v154
	ds_read_b128 v[228:231], v154 offset:1024
	ds_read_b128 v[232:235], v154 offset:2048
	ds_read_b128 v[236:239], v154 offset:3072
	global_load_lds_dwordx4 v[156:157], off
	v_lshl_add_u64 v[156:157], v[160:161], 0, s[6:7]
	s_add_i32 m0, s28, 0x2000
	s_nop 0
	global_load_lds_dwordx4 v[156:157], off
	s_barrier
	s_waitcnt lgkmcnt(0)
	v_mfma_f32_16x16x32_bf16 v[116:119], v[224:227], v[186:189], v[116:119]
	v_mfma_f32_16x16x32_bf16 v[112:115], v[232:235], v[186:189], v[112:115]
	v_mfma_f32_16x16x32_bf16 v[100:103], v[224:227], v[200:203], v[100:103]
	v_mfma_f32_16x16x32_bf16 v[96:99], v[232:235], v[200:203], v[96:99]
	v_mfma_f32_16x16x32_bf16 v[84:87], v[224:227], v[208:211], v[84:87]
	v_mfma_f32_16x16x32_bf16 v[80:83], v[232:235], v[208:211], v[80:83]
	v_mfma_f32_16x16x32_bf16 v[68:71], v[224:227], v[216:219], v[68:71]
	v_mfma_f32_16x16x32_bf16 v[64:67], v[232:235], v[216:219], v[64:67]
	v_mfma_f32_16x16x32_bf16 v[116:119], v[228:231], v[196:199], v[116:119]
	v_mfma_f32_16x16x32_bf16 v[112:115], v[236:239], v[196:199], v[112:115]
	v_mfma_f32_16x16x32_bf16 v[100:103], v[228:231], v[204:207], v[100:103]
	v_mfma_f32_16x16x32_bf16 v[96:99], v[236:239], v[204:207], v[96:99]
	v_mfma_f32_16x16x32_bf16 v[84:87], v[228:231], v[212:215], v[84:87]
	v_mfma_f32_16x16x32_bf16 v[80:83], v[236:239], v[212:215], v[80:83]
	v_mfma_f32_16x16x32_bf16 v[68:71], v[228:231], v[220:223], v[68:71]
	v_mfma_f32_16x16x32_bf16 v[64:67], v[236:239], v[220:223], v[64:67]
	s_mov_b32 m0, s53
	v_lshl_add_u64 v[156:157], v[164:165], 0, s[6:7]
	s_barrier
	ds_read_b128 v[186:189], v171 offset:49152
	ds_read_b128 v[196:199], v171 offset:50176
	ds_read_b128 v[200:203], v171 offset:51200
	ds_read_b128 v[204:207], v171 offset:52224
	ds_read_b128 v[208:211], v171 offset:53248
	ds_read_b128 v[212:215], v171 offset:54272
	ds_read_b128 v[216:219], v171 offset:55296
	ds_read_b128 v[220:223], v171 offset:56320
	global_load_lds_dwordx4 v[156:157], off
	v_lshl_add_u64 v[156:157], v[168:169], 0, s[6:7]
	s_mov_b32 m0, s54
	s_nop 0
	global_load_lds_dwordx4 v[156:157], off
	s_barrier
	s_waitcnt lgkmcnt(0)
	v_mfma_f32_16x16x32_bf16 v[60:63], v[146:149], v[186:189], v[60:63]
	v_mfma_f32_16x16x32_bf16 v[56:59], v[178:181], v[186:189], v[56:59]
	v_mfma_f32_16x16x32_bf16 v[44:47], v[146:149], v[200:203], v[44:47]
	v_mfma_f32_16x16x32_bf16 v[40:43], v[178:181], v[200:203], v[40:43]
	v_mfma_f32_16x16x32_bf16 v[28:31], v[146:149], v[208:211], v[28:31]
	v_mfma_f32_16x16x32_bf16 v[24:27], v[178:181], v[208:211], v[24:27]
	v_mfma_f32_16x16x32_bf16 v[12:15], v[146:149], v[216:219], v[12:15]
	v_mfma_f32_16x16x32_bf16 v[8:11], v[178:181], v[216:219], v[8:11]
	v_mfma_f32_16x16x32_bf16 v[60:63], v[150:153], v[196:199], v[60:63]
	v_mfma_f32_16x16x32_bf16 v[56:59], v[182:185], v[196:199], v[56:59]
	v_mfma_f32_16x16x32_bf16 v[44:47], v[150:153], v[204:207], v[44:47]
	v_mfma_f32_16x16x32_bf16 v[40:43], v[182:185], v[204:207], v[40:43]
	v_mfma_f32_16x16x32_bf16 v[28:31], v[150:153], v[212:215], v[28:31]
	v_mfma_f32_16x16x32_bf16 v[24:27], v[182:185], v[212:215], v[24:27]
	v_mfma_f32_16x16x32_bf16 v[12:15], v[150:153], v[220:223], v[12:15]
	v_mfma_f32_16x16x32_bf16 v[8:11], v[182:185], v[220:223], v[8:11]
	s_barrier
	s_add_u32 s42, s42, 0x40080
	s_addc_u32 s43, s43, 0
	s_add_i32 s28, s29, s11
	v_lshl_add_u64 v[146:147], s[42:43], 0, v[132:133]
	s_mov_b32 m0, s28
	s_nop 0
	global_load_lds_dwordx4 v[146:147], off
	v_lshl_add_u64 v[146:147], s[42:43], 0, v[128:129]
	s_add_i32 m0, s28, 0x2000
	s_nop 0
	global_load_lds_dwordx4 v[146:147], off
	s_waitcnt vmcnt(6)
	s_barrier
	v_mfma_f32_16x16x32_bf16 v[52:55], v[224:227], v[186:189], v[52:55]
	v_mfma_f32_16x16x32_bf16 v[48:51], v[232:235], v[186:189], v[48:51]
	v_mfma_f32_16x16x32_bf16 v[36:39], v[224:227], v[200:203], v[36:39]
	v_mfma_f32_16x16x32_bf16 v[32:35], v[232:235], v[200:203], v[32:35]
	v_mfma_f32_16x16x32_bf16 v[20:23], v[224:227], v[208:211], v[20:23]
	v_mfma_f32_16x16x32_bf16 v[16:19], v[232:235], v[208:211], v[16:19]
	v_mfma_f32_16x16x32_bf16 v[4:7], v[224:227], v[216:219], v[4:7]
	v_mfma_f32_16x16x32_bf16 v[0:3], v[232:235], v[216:219], v[0:3]
	v_mfma_f32_16x16x32_bf16 v[52:55], v[228:231], v[196:199], v[52:55]
	v_mfma_f32_16x16x32_bf16 v[48:51], v[236:239], v[196:199], v[48:51]
	v_mfma_f32_16x16x32_bf16 v[36:39], v[228:231], v[204:207], v[36:39]
	v_mfma_f32_16x16x32_bf16 v[32:35], v[236:239], v[204:207], v[32:35]
	v_mfma_f32_16x16x32_bf16 v[20:23], v[228:231], v[212:215], v[20:23]
	v_mfma_f32_16x16x32_bf16 v[16:19], v[236:239], v[212:215], v[16:19]
	v_mfma_f32_16x16x32_bf16 v[4:7], v[228:231], v[220:223], v[4:7]
	v_mfma_f32_16x16x32_bf16 v[0:3], v[236:239], v[220:223], v[0:3]
	s_add_i32 s64, s64, 2
	s_add_u32 s0, s0, 0x100
	s_addc_u32 s1, s1, 0
	s_add_u32 s62, s62, 0x100
	s_addc_u32 s63, s63, 0
	s_cmp_gt_u32 s64, 13
	s_barrier
	s_cbranch_scc0 .LBB0_1093
	v_lshl_add_u32 v168, s4, 8, v155
	v_or_b32_e32 v164, 16, v168
	v_or_b32_e32 v160, 32, v168
	v_or_b32_e32 v156, 48, v168
	v_add_u32_e32 v152, 0x80, v168
	v_add_u32_e32 v150, 0x90, v168
	v_add_u32_e32 v148, 0xa0, v168
	v_add_u32_e32 v146, 0xb0, v168
	v_lshl_or_b32 v172, s5, 7, v163
	v_mov_b32_e32 v178, v240
	v_mov_b32_e32 v179, v240
	v_mov_b32_e32 v154, v241
	s_and_b32 s0, s36, 0x7f
	v_lshl_add_u32 v228, s0, 8, v155
	v_mov_b32_e32 v229, 0
	v_lshlrev_b32_e32 v228, 6, v228
	v_lshl_add_u64 v[230:231], v[136:137], 0, v[228:229]
	v_mov_b32_e32 v228, 0x2000
	v_lshl_add_u64 v[232:233], v[230:231], 0, v[228:229]
	global_load_dwordx4 v[216:219], v[230:231], off
	global_load_dwordx4 v[220:223], v[230:231], off offset:1024
	global_load_dwordx4 v[224:227], v[230:231], off offset:2048
	global_load_dwordx4 v[196:199], v[230:231], off offset:3072
	global_load_dwordx4 v[200:203], v[232:233], off
	global_load_dwordx4 v[204:207], v[232:233], off offset:1024
	global_load_dwordx4 v[208:211], v[232:233], off offset:2048
	global_load_dwordx4 v[212:215], v[232:233], off offset:3072
	v_pk_mul_f32 v[124:125], v[124:125], v[178:179] op_sel_hi:[1,0]
	v_pk_mul_f32 v[126:127], v[126:127], v[178:179] op_sel_hi:[1,0]
	v_mul_f32_e32 v147, 0xbfb8aa3b, v124
	v_exp_f32_e32 v147, v147
	v_mul_f32_e32 v149, 0xbfb8aa3b, v125
	v_exp_f32_e32 v149, v149
	v_mul_f32_e32 v151, 0xbfb8aa3b, v127
	v_add_f32_e32 v147, 1.0, v147
	v_rcp_f32_e32 v180, v147
	v_add_f32_e32 v147, 1.0, v149
	v_mul_f32_e32 v149, 0xbfb8aa3b, v126
	v_exp_f32_e32 v149, v149
	v_exp_f32_e32 v151, v151
	v_rcp_f32_e32 v181, v147
	v_pk_mul_f32 v[116:117], v[116:117], v[178:179] op_sel_hi:[1,0]
	v_add_f32_e32 v147, 1.0, v149
	v_rcp_f32_e32 v182, v147
	v_add_f32_e32 v147, 1.0, v151
	v_rcp_f32_e32 v183, v147
	v_pk_mul_f32 v[124:125], v[124:125], v[180:181]
	v_pk_mul_f32 v[120:121], v[120:121], v[178:179] op_sel_hi:[1,0]
	v_pk_mul_f32 v[116:117], v[116:117], v[124:125]
	v_pk_mul_f32 v[124:125], v[126:127], v[182:183]
	v_mul_f32_e32 v126, 0xbfb8aa3b, v120
	v_exp_f32_e32 v126, v126
	v_pk_mul_f32 v[118:119], v[118:119], v[178:179] op_sel_hi:[1,0]
	v_pk_mul_f32 v[122:123], v[122:123], v[178:179] op_sel_hi:[1,0]
	v_pk_mul_f32 v[118:119], v[118:119], v[124:125]
	v_mul_f32_e32 v124, 0xbfb8aa3b, v121
	v_exp_f32_e32 v125, v124
	v_add_f32_e32 v124, 1.0, v126
	v_mul_f32_e32 v126, 0xbfb8aa3b, v122
	v_mul_f32_e32 v127, 0xbfb8aa3b, v123
	v_exp_f32_e32 v126, v126
	v_exp_f32_e32 v127, v127
	v_add_f32_e32 v125, 1.0, v125
	v_rcp_f32_e32 v124, v124
	v_rcp_f32_e32 v125, v125
	v_add_f32_e32 v126, 1.0, v126
	v_add_f32_e32 v127, 1.0, v127
	v_rcp_f32_e32 v126, v126
	v_rcp_f32_e32 v127, v127
	v_pk_mul_f32 v[112:113], v[112:113], v[178:179] op_sel_hi:[1,0]
	v_pk_mul_f32 v[120:121], v[120:121], v[124:125]
	v_pk_mul_f32 v[114:115], v[114:115], v[178:179] op_sel_hi:[1,0]
	v_pk_mul_f32 v[112:113], v[112:113], v[120:121]
	v_pk_mul_f32 v[120:121], v[122:123], v[126:127]
	v_ashrrev_i32_e32 v173, 31, v172
	v_pk_mul_f32 v[114:115], v[114:115], v[120:121]
	v_cvt_pk_bf16_f32 v116, v116, v117
	v_cvt_pk_bf16_f32 v117, v118, v119
	v_cvt_pk_bf16_f32 v118, v112, v113
	v_mov_b64_e32 v[112:113], s[20:21]
	v_cvt_pk_bf16_f32 v119, v114, v115
	v_mad_i64_i32 v[120:121], s[0:1], v168, s59, v[112:113]
	v_lshlrev_b64 v[114:115], 1, v[172:173]
	v_lshl_add_u64 v[120:121], v[120:121], 0, v[114:115]
	v_pk_mul_f32 v[108:109], v[108:109], v[176:177] op_sel_hi:[1,0]
	global_store_dwordx4 v[120:121], v[116:119], off
	v_mul_f32_e32 v122, 0xbfb8aa3b, v108
	v_pk_mul_f32 v[110:111], v[110:111], v[176:177] op_sel_hi:[1,0]
	v_mul_f32_e32 v116, 0xbfb8aa3b, v109
	v_exp_f32_e32 v122, v122
	v_exp_f32_e32 v117, v116
	v_mul_f32_e32 v118, 0xbfb8aa3b, v110
	v_mul_f32_e32 v119, 0xbfb8aa3b, v111
	v_exp_f32_e32 v118, v118
	v_exp_f32_e32 v119, v119
	v_add_f32_e32 v116, 1.0, v122
	v_add_f32_e32 v117, 1.0, v117
	v_rcp_f32_e32 v116, v116
	v_rcp_f32_e32 v117, v117
	v_add_f32_e32 v118, 1.0, v118
	v_add_f32_e32 v119, 1.0, v119
	v_rcp_f32_e32 v118, v118
	v_rcp_f32_e32 v119, v119
	v_pk_mul_f32 v[100:101], v[100:101], v[176:177] op_sel_hi:[1,0]
	v_pk_mul_f32 v[108:109], v[108:109], v[116:117]
	v_pk_mul_f32 v[104:105], v[104:105], v[176:177] op_sel_hi:[1,0]
	v_pk_mul_f32 v[100:101], v[100:101], v[108:109]
	v_pk_mul_f32 v[108:109], v[110:111], v[118:119]
	v_mul_f32_e32 v110, 0xbfb8aa3b, v104
	v_exp_f32_e32 v110, v110
	v_pk_mul_f32 v[102:103], v[102:103], v[176:177] op_sel_hi:[1,0]
	v_pk_mul_f32 v[106:107], v[106:107], v[176:177] op_sel_hi:[1,0]
	v_pk_mul_f32 v[102:103], v[102:103], v[108:109]
	v_mul_f32_e32 v108, 0xbfb8aa3b, v105
	v_exp_f32_e32 v109, v108
	v_add_f32_e32 v108, 1.0, v110
	v_mul_f32_e32 v110, 0xbfb8aa3b, v106
	v_mul_f32_e32 v111, 0xbfb8aa3b, v107
	v_exp_f32_e32 v110, v110
	v_exp_f32_e32 v111, v111
	v_add_f32_e32 v109, 1.0, v109
	v_rcp_f32_e32 v108, v108
	v_rcp_f32_e32 v109, v109
	v_add_f32_e32 v110, 1.0, v110
	v_add_f32_e32 v111, 1.0, v111
	v_rcp_f32_e32 v110, v110
	v_rcp_f32_e32 v111, v111
	v_pk_mul_f32 v[96:97], v[96:97], v[176:177] op_sel_hi:[1,0]
	v_pk_mul_f32 v[104:105], v[104:105], v[108:109]
	v_pk_mul_f32 v[92:93], v[92:93], v[174:175] op_sel_hi:[1,0]
	v_pk_mul_f32 v[104:105], v[96:97], v[104:105]
	v_pk_mul_f32 v[96:97], v[98:99], v[176:177] op_sel_hi:[1,0]
	v_pk_mul_f32 v[98:99], v[106:107], v[110:111]
	v_pk_mul_f32 v[94:95], v[94:95], v[174:175] op_sel_hi:[1,0]
	v_pk_mul_f32 v[106:107], v[96:97], v[98:99]
	v_cvt_pk_bf16_f32 v96, v100, v101
	v_mad_i64_i32 v[100:101], s[0:1], v164, s59, v[112:113]
	v_cvt_pk_bf16_f32 v97, v102, v103
	v_cvt_pk_bf16_f32 v98, v104, v105
	v_cvt_pk_bf16_f32 v99, v106, v107
	v_lshl_add_u64 v[100:101], v[100:101], 0, v[114:115]
	v_mul_f32_e32 v102, 0xbfb8aa3b, v92
	global_store_dwordx4 v[100:101], v[96:99], off
	v_exp_f32_e32 v102, v102
	v_pk_mul_f32 v[84:85], v[84:85], v[174:175] op_sel_hi:[1,0]
	v_mul_f32_e32 v96, 0xbfb8aa3b, v93
	v_exp_f32_e32 v97, v96
	v_mul_f32_e32 v98, 0xbfb8aa3b, v94
	v_mul_f32_e32 v99, 0xbfb8aa3b, v95
	v_exp_f32_e32 v98, v98
	v_exp_f32_e32 v99, v99
	v_add_f32_e32 v96, 1.0, v102
	v_add_f32_e32 v97, 1.0, v97
	v_rcp_f32_e32 v96, v96
	v_rcp_f32_e32 v97, v97
	v_add_f32_e32 v98, 1.0, v98
	v_add_f32_e32 v99, 1.0, v99
	v_rcp_f32_e32 v98, v98
	v_rcp_f32_e32 v99, v99
	v_pk_mul_f32 v[92:93], v[92:93], v[96:97]
	v_pk_mul_f32 v[88:89], v[88:89], v[174:175] op_sel_hi:[1,0]
	v_pk_mul_f32 v[84:85], v[84:85], v[92:93]
	v_pk_mul_f32 v[92:93], v[94:95], v[98:99]
	v_mul_f32_e32 v94, 0xbfb8aa3b, v88
	v_exp_f32_e32 v94, v94
	v_pk_mul_f32 v[86:87], v[86:87], v[174:175] op_sel_hi:[1,0]
	v_pk_mul_f32 v[90:91], v[90:91], v[174:175] op_sel_hi:[1,0]
	v_pk_mul_f32 v[86:87], v[86:87], v[92:93]
	v_mul_f32_e32 v92, 0xbfb8aa3b, v89
	v_exp_f32_e32 v93, v92
	v_add_f32_e32 v92, 1.0, v94
	v_mul_f32_e32 v94, 0xbfb8aa3b, v90
	v_mul_f32_e32 v95, 0xbfb8aa3b, v91
	v_exp_f32_e32 v94, v94
	v_exp_f32_e32 v95, v95
	v_add_f32_e32 v93, 1.0, v93
	v_rcp_f32_e32 v92, v92
	v_rcp_f32_e32 v93, v93
	v_add_f32_e32 v94, 1.0, v94
	v_add_f32_e32 v95, 1.0, v95
	v_rcp_f32_e32 v94, v94
	v_rcp_f32_e32 v95, v95
	v_pk_mul_f32 v[80:81], v[80:81], v[174:175] op_sel_hi:[1,0]
	v_pk_mul_f32 v[88:89], v[88:89], v[92:93]
	v_pk_mul_f32 v[76:77], v[76:77], v[170:171] op_sel_hi:[1,0]
	v_pk_mul_f32 v[88:89], v[80:81], v[88:89]
	v_pk_mul_f32 v[80:81], v[82:83], v[174:175] op_sel_hi:[1,0]
	v_pk_mul_f32 v[82:83], v[90:91], v[94:95]
	v_pk_mul_f32 v[78:79], v[78:79], v[170:171] op_sel_hi:[1,0]
	v_pk_mul_f32 v[90:91], v[80:81], v[82:83]
	v_cvt_pk_bf16_f32 v80, v84, v85
	v_mad_i64_i32 v[84:85], s[0:1], v160, s59, v[112:113]
	v_cvt_pk_bf16_f32 v81, v86, v87
	v_cvt_pk_bf16_f32 v82, v88, v89
	v_cvt_pk_bf16_f32 v83, v90, v91
	v_lshl_add_u64 v[84:85], v[84:85], 0, v[114:115]
	v_mul_f32_e32 v86, 0xbfb8aa3b, v76
	global_store_dwordx4 v[84:85], v[80:83], off
	v_exp_f32_e32 v86, v86
	v_pk_mul_f32 v[68:69], v[68:69], v[170:171] op_sel_hi:[1,0]
	v_mul_f32_e32 v80, 0xbfb8aa3b, v77
	v_exp_f32_e32 v81, v80
	v_mul_f32_e32 v82, 0xbfb8aa3b, v78
	v_mul_f32_e32 v83, 0xbfb8aa3b, v79
	v_exp_f32_e32 v82, v82
	v_exp_f32_e32 v83, v83
	v_add_f32_e32 v80, 1.0, v86
	v_add_f32_e32 v81, 1.0, v81
	v_rcp_f32_e32 v80, v80
	v_rcp_f32_e32 v81, v81
	v_add_f32_e32 v82, 1.0, v82
	v_add_f32_e32 v83, 1.0, v83
	v_rcp_f32_e32 v82, v82
	v_rcp_f32_e32 v83, v83
	v_pk_mul_f32 v[76:77], v[76:77], v[80:81]
	v_pk_mul_f32 v[72:73], v[72:73], v[170:171] op_sel_hi:[1,0]
	v_pk_mul_f32 v[68:69], v[68:69], v[76:77]
	v_pk_mul_f32 v[76:77], v[78:79], v[82:83]
	v_mul_f32_e32 v78, 0xbfb8aa3b, v72
	v_exp_f32_e32 v78, v78
	v_pk_mul_f32 v[70:71], v[70:71], v[170:171] op_sel_hi:[1,0]
	v_pk_mul_f32 v[74:75], v[74:75], v[170:171] op_sel_hi:[1,0]
	v_pk_mul_f32 v[70:71], v[70:71], v[76:77]
	v_mul_f32_e32 v76, 0xbfb8aa3b, v73
	v_exp_f32_e32 v77, v76
	v_add_f32_e32 v76, 1.0, v78
	v_mul_f32_e32 v78, 0xbfb8aa3b, v74
	v_mul_f32_e32 v79, 0xbfb8aa3b, v75
	v_exp_f32_e32 v78, v78
	v_exp_f32_e32 v79, v79
	v_add_f32_e32 v77, 1.0, v77
	v_rcp_f32_e32 v76, v76
	v_rcp_f32_e32 v77, v77
	v_add_f32_e32 v78, 1.0, v78
	v_add_f32_e32 v79, 1.0, v79
	v_rcp_f32_e32 v78, v78
	v_rcp_f32_e32 v79, v79
	v_pk_mul_f32 v[64:65], v[64:65], v[170:171] op_sel_hi:[1,0]
	v_pk_mul_f32 v[72:73], v[72:73], v[76:77]
	v_pk_mul_f32 v[60:61], v[60:61], v[166:167] op_sel_hi:[1,0]
	v_pk_mul_f32 v[72:73], v[64:65], v[72:73]
	v_pk_mul_f32 v[64:65], v[66:67], v[170:171] op_sel_hi:[1,0]
	v_pk_mul_f32 v[66:67], v[74:75], v[78:79]
	v_pk_mul_f32 v[62:63], v[62:63], v[166:167] op_sel_hi:[1,0]
	v_pk_mul_f32 v[74:75], v[64:65], v[66:67]
	v_cvt_pk_bf16_f32 v64, v68, v69
	v_mad_i64_i32 v[68:69], s[0:1], v156, s59, v[112:113]
	v_cvt_pk_bf16_f32 v65, v70, v71
	v_cvt_pk_bf16_f32 v66, v72, v73
	v_cvt_pk_bf16_f32 v67, v74, v75
	v_lshl_add_u64 v[68:69], v[68:69], 0, v[114:115]
	v_mul_f32_e32 v70, 0xbfb8aa3b, v60
	global_store_dwordx4 v[68:69], v[64:67], off
	v_exp_f32_e32 v70, v70
	v_pk_mul_f32 v[52:53], v[52:53], v[166:167] op_sel_hi:[1,0]
	v_mul_f32_e32 v64, 0xbfb8aa3b, v61
	v_exp_f32_e32 v65, v64
	v_mul_f32_e32 v66, 0xbfb8aa3b, v62
	v_mul_f32_e32 v67, 0xbfb8aa3b, v63
	v_exp_f32_e32 v66, v66
	v_exp_f32_e32 v67, v67
	v_add_f32_e32 v64, 1.0, v70
	v_add_f32_e32 v65, 1.0, v65
	v_rcp_f32_e32 v64, v64
	v_rcp_f32_e32 v65, v65
	v_add_f32_e32 v66, 1.0, v66
	v_add_f32_e32 v67, 1.0, v67
	v_rcp_f32_e32 v66, v66
	v_rcp_f32_e32 v67, v67
	v_pk_mul_f32 v[60:61], v[60:61], v[64:65]
	v_pk_mul_f32 v[56:57], v[56:57], v[166:167] op_sel_hi:[1,0]
	v_pk_mul_f32 v[52:53], v[52:53], v[60:61]
	v_pk_mul_f32 v[60:61], v[62:63], v[66:67]
	v_mul_f32_e32 v62, 0xbfb8aa3b, v56
	v_exp_f32_e32 v62, v62
	v_pk_mul_f32 v[54:55], v[54:55], v[166:167] op_sel_hi:[1,0]
	v_pk_mul_f32 v[58:59], v[58:59], v[166:167] op_sel_hi:[1,0]
	v_pk_mul_f32 v[54:55], v[54:55], v[60:61]
	v_mul_f32_e32 v60, 0xbfb8aa3b, v57
	v_exp_f32_e32 v61, v60
	v_add_f32_e32 v60, 1.0, v62
	v_mul_f32_e32 v62, 0xbfb8aa3b, v58
	v_mul_f32_e32 v63, 0xbfb8aa3b, v59
	v_exp_f32_e32 v62, v62
	v_exp_f32_e32 v63, v63
	v_add_f32_e32 v61, 1.0, v61
	v_rcp_f32_e32 v60, v60
	v_rcp_f32_e32 v61, v61
	v_add_f32_e32 v62, 1.0, v62
	v_add_f32_e32 v63, 1.0, v63
	v_rcp_f32_e32 v62, v62
	v_rcp_f32_e32 v63, v63
	v_pk_mul_f32 v[48:49], v[48:49], v[166:167] op_sel_hi:[1,0]
	v_pk_mul_f32 v[56:57], v[56:57], v[60:61]
	v_pk_mul_f32 v[44:45], v[44:45], v[162:163] op_sel_hi:[1,0]
	v_pk_mul_f32 v[56:57], v[48:49], v[56:57]
	v_pk_mul_f32 v[48:49], v[50:51], v[166:167] op_sel_hi:[1,0]
	v_pk_mul_f32 v[50:51], v[58:59], v[62:63]
	v_pk_mul_f32 v[46:47], v[46:47], v[162:163] op_sel_hi:[1,0]
	v_pk_mul_f32 v[58:59], v[48:49], v[50:51]
	v_cvt_pk_bf16_f32 v48, v52, v53
	v_mad_i64_i32 v[52:53], s[0:1], v152, s59, v[112:113]
	v_cvt_pk_bf16_f32 v49, v54, v55
	v_cvt_pk_bf16_f32 v50, v56, v57
	v_cvt_pk_bf16_f32 v51, v58, v59
	v_lshl_add_u64 v[52:53], v[52:53], 0, v[114:115]
	v_mul_f32_e32 v54, 0xbfb8aa3b, v44
	global_store_dwordx4 v[52:53], v[48:51], off
	v_exp_f32_e32 v54, v54
	v_pk_mul_f32 v[36:37], v[36:37], v[162:163] op_sel_hi:[1,0]
	v_mul_f32_e32 v48, 0xbfb8aa3b, v45
	v_exp_f32_e32 v49, v48
	v_mul_f32_e32 v50, 0xbfb8aa3b, v46
	v_mul_f32_e32 v51, 0xbfb8aa3b, v47
	v_exp_f32_e32 v50, v50
	v_exp_f32_e32 v51, v51
	v_add_f32_e32 v48, 1.0, v54
	v_add_f32_e32 v49, 1.0, v49
	v_rcp_f32_e32 v48, v48
	v_rcp_f32_e32 v49, v49
	v_add_f32_e32 v50, 1.0, v50
	v_add_f32_e32 v51, 1.0, v51
	v_rcp_f32_e32 v50, v50
	v_rcp_f32_e32 v51, v51
	v_pk_mul_f32 v[44:45], v[44:45], v[48:49]
	v_pk_mul_f32 v[40:41], v[40:41], v[162:163] op_sel_hi:[1,0]
	v_pk_mul_f32 v[36:37], v[36:37], v[44:45]
	v_pk_mul_f32 v[44:45], v[46:47], v[50:51]
	v_mul_f32_e32 v46, 0xbfb8aa3b, v40
	v_exp_f32_e32 v46, v46
	v_pk_mul_f32 v[38:39], v[38:39], v[162:163] op_sel_hi:[1,0]
	v_pk_mul_f32 v[42:43], v[42:43], v[162:163] op_sel_hi:[1,0]
	v_pk_mul_f32 v[38:39], v[38:39], v[44:45]
	v_mul_f32_e32 v44, 0xbfb8aa3b, v41
	v_exp_f32_e32 v45, v44
	v_add_f32_e32 v44, 1.0, v46
	v_mul_f32_e32 v46, 0xbfb8aa3b, v42
	v_mul_f32_e32 v47, 0xbfb8aa3b, v43
	v_exp_f32_e32 v46, v46
	v_exp_f32_e32 v47, v47
	v_add_f32_e32 v45, 1.0, v45
	v_rcp_f32_e32 v44, v44
	v_rcp_f32_e32 v45, v45
	v_add_f32_e32 v46, 1.0, v46
	v_add_f32_e32 v47, 1.0, v47
	v_rcp_f32_e32 v46, v46
	v_rcp_f32_e32 v47, v47
	v_pk_mul_f32 v[32:33], v[32:33], v[162:163] op_sel_hi:[1,0]
	v_pk_mul_f32 v[40:41], v[40:41], v[44:45]
	v_pk_mul_f32 v[28:29], v[28:29], v[158:159] op_sel_hi:[1,0]
	v_pk_mul_f32 v[40:41], v[32:33], v[40:41]
	v_pk_mul_f32 v[32:33], v[34:35], v[162:163] op_sel_hi:[1,0]
	v_pk_mul_f32 v[34:35], v[42:43], v[46:47]
	v_pk_mul_f32 v[30:31], v[30:31], v[158:159] op_sel_hi:[1,0]
	v_pk_mul_f32 v[42:43], v[32:33], v[34:35]
	v_cvt_pk_bf16_f32 v32, v36, v37
	v_mad_i64_i32 v[36:37], s[0:1], v150, s59, v[112:113]
	v_cvt_pk_bf16_f32 v33, v38, v39
	v_cvt_pk_bf16_f32 v34, v40, v41
	v_cvt_pk_bf16_f32 v35, v42, v43
	v_lshl_add_u64 v[36:37], v[36:37], 0, v[114:115]
	v_mul_f32_e32 v38, 0xbfb8aa3b, v28
	global_store_dwordx4 v[36:37], v[32:35], off
	v_exp_f32_e32 v38, v38
	v_pk_mul_f32 v[20:21], v[20:21], v[158:159] op_sel_hi:[1,0]
	v_mul_f32_e32 v32, 0xbfb8aa3b, v29
	v_exp_f32_e32 v33, v32
	v_mul_f32_e32 v34, 0xbfb8aa3b, v30
	v_mul_f32_e32 v35, 0xbfb8aa3b, v31
	v_exp_f32_e32 v34, v34
	v_exp_f32_e32 v35, v35
	v_add_f32_e32 v32, 1.0, v38
	v_add_f32_e32 v33, 1.0, v33
	v_rcp_f32_e32 v32, v32
	v_rcp_f32_e32 v33, v33
	v_add_f32_e32 v34, 1.0, v34
	v_add_f32_e32 v35, 1.0, v35
	v_rcp_f32_e32 v34, v34
	v_rcp_f32_e32 v35, v35
	v_pk_mul_f32 v[28:29], v[28:29], v[32:33]
	v_pk_mul_f32 v[24:25], v[24:25], v[158:159] op_sel_hi:[1,0]
	v_pk_mul_f32 v[20:21], v[20:21], v[28:29]
	v_pk_mul_f32 v[28:29], v[30:31], v[34:35]
	v_mul_f32_e32 v30, 0xbfb8aa3b, v24
	v_exp_f32_e32 v30, v30
	v_pk_mul_f32 v[22:23], v[22:23], v[158:159] op_sel_hi:[1,0]
	v_pk_mul_f32 v[26:27], v[26:27], v[158:159] op_sel_hi:[1,0]
	v_pk_mul_f32 v[22:23], v[22:23], v[28:29]
	v_mul_f32_e32 v28, 0xbfb8aa3b, v25
	v_exp_f32_e32 v29, v28
	v_add_f32_e32 v28, 1.0, v30
	v_mul_f32_e32 v30, 0xbfb8aa3b, v26
	v_mul_f32_e32 v31, 0xbfb8aa3b, v27
	v_exp_f32_e32 v30, v30
	v_exp_f32_e32 v31, v31
	v_add_f32_e32 v29, 1.0, v29
	v_rcp_f32_e32 v28, v28
	v_rcp_f32_e32 v29, v29
	v_add_f32_e32 v30, 1.0, v30
	v_add_f32_e32 v31, 1.0, v31
	v_rcp_f32_e32 v30, v30
	v_rcp_f32_e32 v31, v31
	v_pk_mul_f32 v[16:17], v[16:17], v[158:159] op_sel_hi:[1,0]
	v_pk_mul_f32 v[24:25], v[24:25], v[28:29]
	v_pk_mul_f32 v[12:13], v[12:13], v[154:155] op_sel_hi:[1,0]
	v_pk_mul_f32 v[24:25], v[16:17], v[24:25]
	v_pk_mul_f32 v[16:17], v[18:19], v[158:159] op_sel_hi:[1,0]
	v_pk_mul_f32 v[18:19], v[26:27], v[30:31]
	v_pk_mul_f32 v[14:15], v[14:15], v[154:155] op_sel_hi:[1,0]
	v_pk_mul_f32 v[26:27], v[16:17], v[18:19]
	v_cvt_pk_bf16_f32 v16, v20, v21
	v_mad_i64_i32 v[20:21], s[0:1], v148, s59, v[112:113]
	v_cvt_pk_bf16_f32 v17, v22, v23
	v_cvt_pk_bf16_f32 v18, v24, v25
	v_cvt_pk_bf16_f32 v19, v26, v27
	v_lshl_add_u64 v[20:21], v[20:21], 0, v[114:115]
	v_mul_f32_e32 v22, 0xbfb8aa3b, v12
	global_store_dwordx4 v[20:21], v[16:19], off
	v_exp_f32_e32 v22, v22
	v_pk_mul_f32 v[4:5], v[4:5], v[154:155] op_sel_hi:[1,0]
	v_mul_f32_e32 v16, 0xbfb8aa3b, v13
	v_exp_f32_e32 v17, v16
	v_mul_f32_e32 v18, 0xbfb8aa3b, v14
	v_mul_f32_e32 v19, 0xbfb8aa3b, v15
	v_exp_f32_e32 v18, v18
	v_exp_f32_e32 v19, v19
	v_add_f32_e32 v16, 1.0, v22
	v_add_f32_e32 v17, 1.0, v17
	v_rcp_f32_e32 v16, v16
	v_rcp_f32_e32 v17, v17
	v_add_f32_e32 v18, 1.0, v18
	v_add_f32_e32 v19, 1.0, v19
	v_rcp_f32_e32 v18, v18
	v_rcp_f32_e32 v19, v19
	v_pk_mul_f32 v[12:13], v[12:13], v[16:17]
	v_pk_mul_f32 v[8:9], v[8:9], v[154:155] op_sel_hi:[1,0]
	v_pk_mul_f32 v[4:5], v[4:5], v[12:13]
	v_pk_mul_f32 v[12:13], v[14:15], v[18:19]
	v_mul_f32_e32 v14, 0xbfb8aa3b, v8
	v_exp_f32_e32 v14, v14
	v_pk_mul_f32 v[6:7], v[6:7], v[154:155] op_sel_hi:[1,0]
	v_pk_mul_f32 v[10:11], v[10:11], v[154:155] op_sel_hi:[1,0]
	v_pk_mul_f32 v[6:7], v[6:7], v[12:13]
	v_mul_f32_e32 v12, 0xbfb8aa3b, v9
	v_exp_f32_e32 v13, v12
	v_add_f32_e32 v12, 1.0, v14
	v_mul_f32_e32 v14, 0xbfb8aa3b, v10
	v_mul_f32_e32 v15, 0xbfb8aa3b, v11
	v_exp_f32_e32 v14, v14
	v_exp_f32_e32 v15, v15
	v_add_f32_e32 v13, 1.0, v13
	v_rcp_f32_e32 v12, v12
	v_rcp_f32_e32 v13, v13
	v_add_f32_e32 v14, 1.0, v14
	v_add_f32_e32 v15, 1.0, v15
	v_rcp_f32_e32 v14, v14
	v_rcp_f32_e32 v15, v15
	v_pk_mul_f32 v[0:1], v[0:1], v[154:155] op_sel_hi:[1,0]
	v_pk_mul_f32 v[8:9], v[8:9], v[12:13]
	s_and_b64 vcc, exec, s[2:3]
	v_pk_mul_f32 v[8:9], v[0:1], v[8:9]
	v_pk_mul_f32 v[0:1], v[2:3], v[154:155] op_sel_hi:[1,0]
	v_pk_mul_f32 v[2:3], v[10:11], v[14:15]
	s_mov_b32 s5, s12
	v_pk_mul_f32 v[10:11], v[0:1], v[2:3]
	v_cvt_pk_bf16_f32 v0, v4, v5
	v_mad_i64_i32 v[4:5], s[0:1], v146, s59, v[112:113]
	v_cvt_pk_bf16_f32 v1, v6, v7
	v_cvt_pk_bf16_f32 v2, v8, v9
	v_cvt_pk_bf16_f32 v3, v10, v11
	v_lshl_add_u64 v[4:5], v[4:5], 0, v[114:115]
	s_mov_b32 s4, s36
	s_mov_b64 s[42:43], s[40:41]
	s_mov_b64 s[44:45], s[38:39]
	global_store_dwordx4 v[4:5], v[0:3], off
	s_waitcnt vmcnt(8)
	v_xor_b32_e32 v184, 16, v177
	v_xor_b32_e32 v185, 32, v177
	v_lshlrev_b32_e32 v184, 2, v184
	v_lshlrev_b32_e32 v185, 2, v185
	v_mov_b32_e32 v190, s10
	v_pk_add_f32 v[216:217], v[216:217], v[218:219]
	v_pk_add_f32 v[220:221], v[220:221], v[222:223]
	v_pk_add_f32 v[224:225], v[224:225], v[226:227]
	v_pk_add_f32 v[196:197], v[196:197], v[198:199]
	v_pk_add_f32 v[200:201], v[200:201], v[202:203]
	v_pk_add_f32 v[204:205], v[204:205], v[206:207]
	v_pk_add_f32 v[208:209], v[208:209], v[210:211]
	v_pk_add_f32 v[212:213], v[212:213], v[214:215]
	v_add_f32_e32 v216, v216, v217
	v_add_f32_e32 v220, v220, v221
	v_add_f32_e32 v224, v224, v225
	v_add_f32_e32 v196, v196, v197
	v_add_f32_e32 v200, v200, v201
	v_add_f32_e32 v204, v204, v205
	v_add_f32_e32 v208, v208, v209
	v_add_f32_e32 v212, v212, v213
	ds_bpermute_b32 v218, v184, v216
	ds_bpermute_b32 v219, v184, v220
	ds_bpermute_b32 v222, v184, v224
	ds_bpermute_b32 v223, v184, v196
	ds_bpermute_b32 v226, v184, v200
	ds_bpermute_b32 v227, v184, v204
	ds_bpermute_b32 v198, v184, v208
	ds_bpermute_b32 v199, v184, v212
	s_waitcnt lgkmcnt(0)
	v_add_f32_e32 v216, v216, v218
	v_add_f32_e32 v220, v220, v219
	v_add_f32_e32 v224, v224, v222
	v_add_f32_e32 v196, v196, v223
	v_add_f32_e32 v200, v200, v226
	v_add_f32_e32 v204, v204, v227
	v_add_f32_e32 v208, v208, v198
	v_add_f32_e32 v212, v212, v199
	ds_bpermute_b32 v218, v185, v216
	ds_bpermute_b32 v219, v185, v220
	ds_bpermute_b32 v222, v185, v224
	ds_bpermute_b32 v223, v185, v196
	ds_bpermute_b32 v226, v185, v200
	ds_bpermute_b32 v227, v185, v204
	ds_bpermute_b32 v198, v185, v208
	ds_bpermute_b32 v199, v185, v212
	s_waitcnt lgkmcnt(0)
	v_add_f32_e32 v216, v216, v218
	v_add_f32_e32 v220, v220, v219
	v_add_f32_e32 v224, v224, v222
	v_add_f32_e32 v196, v196, v223
	v_add_f32_e32 v200, v200, v226
	v_add_f32_e32 v204, v204, v227
	v_add_f32_e32 v208, v208, v198
	v_add_f32_e32 v212, v212, v199
	v_fma_f32 v216, v216, s8, v190
	v_fma_f32 v220, v220, s8, v190
	v_fma_f32 v224, v224, s8, v190
	v_fma_f32 v196, v196, s8, v190
	v_fma_f32 v200, v200, s8, v190
	v_fma_f32 v204, v204, s8, v190
	v_fma_f32 v208, v208, s8, v190
	v_fma_f32 v212, v212, s8, v190
	v_rsq_f32_e32 v240, v216
	v_rsq_f32_e32 v176, v220
	v_rsq_f32_e32 v174, v224
	v_rsq_f32_e32 v170, v196
	v_rsq_f32_e32 v166, v200
	v_rsq_f32_e32 v162, v204
	v_rsq_f32_e32 v158, v208
	v_rsq_f32_e32 v241, v212
	s_and_b64 vcc, exec, s[2:3]
	s_mov_b32 s5, s12
	s_mov_b32 s4, s36
	s_mov_b32 s98, 1
	s_cbranch_vccz .LBB0_1090
	s_waitcnt vmcnt(0)
	s_cmpk_gt_u32 s9, 0xff
	s_cbranch_scc1 .LBB0_1097
	s_barrier
